# baseline (speedup 1.0000x reference)
; __global__ void __launch_bounds__(NTHREADS) fwd_megakernel(Params p) {
;     ...
;       if (step == 0 || (step == 9 && layer == 0)) {
;         const int cset = (step == 9) ? 2 : (layer == 0 ? 4 : 3);
.LBB0_1264:
	v_readlane_b32 s2, v254, 27
	s_cmp_eq_u32 s2, 0
	s_cbranch_scc1 .LBB0_1266
	v_readlane_b32 s4, v254, 23
	v_readlane_b32 s5, v254, 24
	s_cmp_eq_u32 s2, 9
	s_cselect_b64 s[6:7], -1, 0
	s_cmp_eq_u32 s2, 3
	s_cselect_b64 s[2:3], -1, 0
	s_nop 1
	s_andn2_b64 s[2:3], s[2:3], s[4:5]
	s_or_b64 s[2:3], s[2:3], s[6:7]
	s_and_b64 s[4:5], s[4:5], exec
	s_cselect_b32 s12, 2, 6
	s_branch .LBB0_1267

; __device__ __forceinline__ void convert_set(unsigned char* ws, int set, int gi, int ng, float* lds, int wv_) {
;     ...
;   } else {
;     conv_run(inp(ws, 8) + fw, (u16*)(ws + OFF_W13_11), D_, F_, 1, base, lds, gi, ng, wv_);
;     conv_run(inp(ws, 9) + fw, (u16*)(ws + OFF_W13_11), D_, F_, 2, base, lds, gi, ng, wv_);
;     conv_run(inp(ws, 10) + fw, (u16*)(ws + OFF_W2_11), F_, D_, 0, base, lds, gi, ng, wv_);
.LBB0_1494:
	v_readlane_b32 s8, v254, 27
	s_nop 3
	s_cmp_eq_u32 s8, 0
	s_cbranch_scc0 .Lset3_not0
	v_readlane_b32 s16, v253, 40
	v_readlane_b32 s17, v253, 41
	s_branch .LBB0_1508
.Lset3_not0:
	s_cmp_eq_u32 s8, 9
	s_cbranch_scc0 .Lset3_normal
	s_mov_b64 s[4:5], 0
	s_branch .LBB0_1503

; __device__ __forceinline__ void convert_set(unsigned char* ws, int set, int gi, int ng, float* lds, int wv_) {
;     ...
;     conv_run(inp(ws, 10) + fw, (u16*)(ws + OFF_W2_11), F_, D_, 0, base, lds, gi, ng, wv_);
.LBB0_1503:
	v_readlane_b32 s16, v254, 27
	s_nop 3
	s_cmp_eq_u32 s16, 9
	s_cbranch_scc1 .Lw2_run
	v_readlane_b32 s16, v253, 40
	v_readlane_b32 s17, v253, 41
	s_branch .LBB0_1508
